# UP epilogue: row-shifted conv operands built by one DPP move with zero fill (separate zero moves removed)
# speedup vs baseline: 1.0048x; 1.0048x over previous
.Lmy_u1_nodefer:
	v_mov_b32_dpp v170, v150 row_shr:1 row_mask:0xf bank_mask:0xf bound_ctrl:0
	v_mov_b32_dpp v171, v151 row_shr:1 row_mask:0xf bank_mask:0xf bound_ctrl:0
	v_mov_b32_dpp v106, v162 row_shr:1 row_mask:0xf bank_mask:0xf bound_ctrl:0
	v_mov_b32_dpp v107, v163 row_shr:1 row_mask:0xf bank_mask:0xf bound_ctrl:0
	v_pk_fma_f32 v[170:171], v[74:75], v[170:171], v[78:79]
	v_pk_fma_f32 v[170:171], v[98:99], v[106:107], v[170:171]
	v_pk_fma_f32 v[174:175], v[94:95], v[166:167], v[170:171]
	v_mul_f32_e32 v0, v174, v174
	v_fmamk_f32 v0, v0, 0xbdd2d3e2, v220
	v_mul_f32_e32 v0, v174, v0
	v_exp_f32_e32 v0, v0
	v_mov_b32_dpp v172, v152 row_shr:1 row_mask:0xf bank_mask:0xf bound_ctrl:0
	v_add_f32_e32 v0, 1.0, v0
	v_rcp_f32_e32 v0, v0
	v_mov_b32_dpp v173, v153 row_shr:1 row_mask:0xf bank_mask:0xf bound_ctrl:0
	v_mul_f32_e32 v0, v174, v0
	v_mul_f32_e32 v174, v175, v175
	v_fmamk_f32 v174, v174, 0xbdd2d3e2, v220
	v_mul_f32_e32 v174, v175, v174
	v_exp_f32_e32 v174, v174
	v_mov_b32_dpp v178, v146 row_shr:1 row_mask:0xf bank_mask:0xf bound_ctrl:0
	v_mov_b32_dpp v179, v147 row_shr:1 row_mask:0xf bank_mask:0xf bound_ctrl:0
	v_add_f32_e32 v174, 1.0, v174
	v_rcp_f32_e32 v174, v174
	v_mov_b32_dpp v108, v164 row_shr:1 row_mask:0xf bank_mask:0xf bound_ctrl:0
	v_mov_b32_dpp v109, v165 row_shr:1 row_mask:0xf bank_mask:0xf bound_ctrl:0
	v_pk_fma_f32 v[172:173], v[76:77], v[172:173], v[80:81]
	v_mov_b32_dpp v170, v158 row_shr:1 row_mask:0xf bank_mask:0xf bound_ctrl:0
	v_mov_b32_dpp v171, v159 row_shr:1 row_mask:0xf bank_mask:0xf bound_ctrl:0
	v_pk_fma_f32 v[178:179], v[86:87], v[178:179], v[90:91]
	v_pk_fma_f32 v[172:173], v[100:101], v[108:109], v[172:173]
	v_pk_fma_f32 v[178:179], v[82:83], v[170:171], v[178:179]
	v_pk_fma_f32 v[176:177], v[96:97], v[168:169], v[172:173]
	v_pk_fma_f32 v[178:179], v[70:71], v[154:155], v[178:179]
	v_mul_f32_e32 v174, v175, v174
	v_mul_f32_e32 v0, v0, v178
	v_mul_f32_e32 v174, v174, v179
	v_mul_f32_e32 v175, v177, v177
	v_cvt_pk_bf16_f32 v174, v0, v174
	v_mul_f32_e32 v0, v176, v176
	v_fmamk_f32 v175, v175, 0xbdd2d3e2, v220
	v_fmamk_f32 v0, v0, 0xbdd2d3e2, v220
	v_mul_f32_e32 v175, v177, v175
	v_mul_f32_e32 v0, v176, v0
	v_exp_f32_e32 v175, v175
	v_exp_f32_e32 v0, v0
	v_add_f32_e32 v175, 1.0, v175
	v_add_f32_e32 v0, 1.0, v0
	v_rcp_f32_e32 v175, v175
	v_mov_b32_dpp v180, v148 row_shr:1 row_mask:0xf bank_mask:0xf bound_ctrl:0
	v_mov_b32_dpp v181, v149 row_shr:1 row_mask:0xf bank_mask:0xf bound_ctrl:0
	v_rcp_f32_e32 v0, v0
	v_mov_b32_dpp v172, v160 row_shr:1 row_mask:0xf bank_mask:0xf bound_ctrl:0
	v_mov_b32_dpp v173, v161 row_shr:1 row_mask:0xf bank_mask:0xf bound_ctrl:0
	v_pk_fma_f32 v[180:181], v[88:89], v[180:181], v[92:93]
	v_mul_f32_e32 v175, v177, v175
	v_pk_fma_f32 v[180:181], v[84:85], v[172:173], v[180:181]
	v_mul_f32_e32 v0, v176, v0
	v_pk_fma_f32 v[180:181], v[72:73], v[156:157], v[180:181]
	s_nop 0
	v_mul_f32_e32 v175, v175, v181
	v_mul_f32_e32 v0, v0, v180
	v_cvt_pk_bf16_f32 v175, v0, v175
	s_and_saveexec_b64 s[30:31], s[4:5]
	s_cbranch_execz .LBB0_242
	s_movk_i32 s23, 0xc00
	v_mul_lo_u32 v0, v237, s23
	v_add_lshl_u32 v0, v0, v192, 1
	v_lshl_add_u64 v[176:177], s[8:9], 0, v[0:1]
	global_store_dwordx2 v[176:177], v[174:175], off

.LBB0_244:
	s_or_b64 exec, exec, s[30:31]
	v_pk_fma_f32 v[106:107], v[76:77], v[168:169], v[80:81]
	v_pk_fma_f32 v[108:109], v[74:75], v[166:167], v[78:79]
	v_pk_fma_f32 v[106:107], v[100:101], v[144:145], v[106:107]
	v_pk_fma_f32 v[144:145], v[76:77], v[144:145], v[80:81]
	v_pk_fma_f32 v[108:109], v[98:99], v[142:143], v[108:109]
	v_pk_fma_f32 v[106:107], v[96:97], v[152:153], v[106:107]
	v_pk_fma_f32 v[144:145], v[100:101], v[152:153], v[144:145]
	v_pk_fma_f32 v[152:153], v[86:87], v[154:155], v[90:91]
	v_pk_fma_f32 v[108:109], v[94:95], v[150:151], v[108:109]
	v_pk_fma_f32 v[152:153], v[82:83], v[138:139], v[152:153]
	v_pk_fma_f32 v[138:139], v[86:87], v[138:139], v[90:91]
	v_pk_fma_f32 v[152:153], v[70:71], v[146:147], v[152:153]
	v_pk_fma_f32 v[138:139], v[82:83], v[146:147], v[138:139]
	v_mul_f32_e32 v0, v108, v108
	v_mul_f32_e32 v146, v109, v109
	v_fmamk_f32 v0, v0, 0xbdd2d3e2, v220
	v_fmamk_f32 v146, v146, 0xbdd2d3e2, v220
	v_mul_f32_e32 v0, v108, v0
	v_mul_f32_e32 v146, v109, v146
	v_exp_f32_e32 v0, v0
	v_exp_f32_e32 v146, v146
	v_pk_fma_f32 v[142:143], v[74:75], v[142:143], v[78:79]
	s_movk_i32 s23, 0xc00
	v_add_f32_e32 v0, 1.0, v0
	v_add_f32_e32 v146, 1.0, v146
	v_rcp_f32_e32 v0, v0
	v_rcp_f32_e32 v146, v146
	v_pk_fma_f32 v[142:143], v[98:99], v[150:151], v[142:143]
	v_pk_fma_f32 v[150:151], v[88:89], v[156:157], v[92:93]
	v_mul_f32_e32 v0, v108, v0
	v_mul_f32_e32 v108, v109, v146
	v_mul_f32_e32 v109, v106, v106
	v_mul_f32_e32 v146, v107, v107
	v_fmamk_f32 v109, v109, 0xbdd2d3e2, v220
	v_fmamk_f32 v146, v146, 0xbdd2d3e2, v220
	v_mul_f32_e32 v109, v106, v109
	v_mul_f32_e32 v146, v107, v146
	v_exp_f32_e32 v109, v109
	v_exp_f32_e32 v146, v146
	v_pk_fma_f32 v[150:151], v[84:85], v[140:141], v[150:151]
	v_mul_f32_e32 v0, v152, v0
	v_add_f32_e32 v109, 1.0, v109
	v_add_f32_e32 v146, 1.0, v146
	v_rcp_f32_e32 v109, v109
	v_rcp_f32_e32 v146, v146
	v_mul_f32_e32 v108, v153, v108
	v_pk_fma_f32 v[150:151], v[72:73], v[148:149], v[150:151]
	v_cvt_pk_bf16_f32 v108, v0, v108
	v_mul_f32_e32 v0, v106, v109
	v_mul_f32_e32 v106, v107, v146
	v_mul_f32_e32 v106, v151, v106
	v_pk_fma_f32 v[142:143], v[94:95], v[162:163], v[142:143]
	v_mul_f32_e32 v0, v150, v0
	v_cvt_pk_bf16_f32 v109, v0, v106
	v_mad_u64_u32 v[106:107], s[30:31], v239, s23, v[192:193]
	v_mul_f32_e32 v107, v142, v142
	v_fmamk_f32 v107, v107, 0xbdd2d3e2, v220
	v_mul_f32_e32 v107, v142, v107
	v_exp_f32_e32 v107, v107
	v_mul_f32_e32 v146, v143, v143
	v_fmamk_f32 v146, v146, 0xbdd2d3e2, v220
	v_pk_fma_f32 v[140:141], v[88:89], v[140:141], v[92:93]
	v_add_f32_e32 v107, 1.0, v107
	v_rcp_f32_e32 v107, v107
	v_lshlrev_b32_e32 v0, 1, v106
	v_mul_f32_e32 v146, v143, v146
	v_pk_fma_f32 v[144:145], v[96:97], v[164:165], v[144:145]
	v_pk_fma_f32 v[140:141], v[84:85], v[148:149], v[140:141]
	v_pk_fma_f32 v[138:139], v[70:71], v[158:159], v[138:139]
	v_exp_f32_e32 v148, v146
	v_lshl_add_u64 v[146:147], s[8:9], 0, v[0:1]
	v_mul_f32_e32 v107, v142, v107
	global_store_dwordx2 v[146:147], v[108:109], off
	v_mul_f32_e32 v107, v138, v107
	v_mul_f32_e32 v109, v144, v144
	v_mul_f32_e32 v138, v145, v145
	v_fmamk_f32 v109, v109, 0xbdd2d3e2, v220
	v_fmamk_f32 v138, v138, 0xbdd2d3e2, v220
	v_mul_f32_e32 v109, v144, v109
	v_mul_f32_e32 v138, v145, v138
	v_exp_f32_e32 v109, v109
	v_exp_f32_e32 v138, v138
	v_add_f32_e32 v148, 1.0, v148
	v_rcp_f32_e32 v148, v148
	v_add_f32_e32 v109, 1.0, v109
	v_add_f32_e32 v138, 1.0, v138
	v_rcp_f32_e32 v109, v109
	v_rcp_f32_e32 v138, v138
	v_mul_f32_e32 v108, v143, v148
	v_mul_f32_e32 v108, v139, v108
	v_pk_fma_f32 v[140:141], v[72:73], v[160:161], v[140:141]
	v_cvt_pk_bf16_f32 v108, v107, v108
	v_mul_f32_e32 v107, v144, v109
	v_mul_f32_e32 v109, v145, v138
	v_mul_f32_e32 v107, v140, v107
	v_mul_f32_e32 v109, v141, v109
	v_add_u32_e32 v146, 0xc00, v106
	v_cvt_pk_bf16_f32 v109, v107, v109
	v_lshlrev_b32_e32 v106, 1, v146
	v_mov_b32_e32 v107, v1
	v_lshl_add_u64 v[138:139], s[8:9], 0, v[106:107]
	global_store_dwordx2 v[138:139], v[108:109], off
	v_mov_b32_dpp v140, v130 row_shr:1 row_mask:0xf bank_mask:0xf bound_ctrl:0
	v_mov_b32_dpp v141, v131 row_shr:1 row_mask:0xf bank_mask:0xf bound_ctrl:0
	v_mov_b32_dpp v108, v122 row_shr:1 row_mask:0xf bank_mask:0xf bound_ctrl:0
	v_mov_b32_dpp v109, v123 row_shr:1 row_mask:0xf bank_mask:0xf bound_ctrl:0
	v_pk_fma_f32 v[140:141], v[74:75], v[140:141], v[78:79]
	v_pk_fma_f32 v[140:141], v[98:99], v[108:109], v[140:141]
	v_pk_fma_f32 v[144:145], v[94:95], v[134:135], v[140:141]
	v_mul_f32_e32 v107, v144, v144
	v_mul_f32_e32 v147, v145, v145
	v_fmamk_f32 v107, v107, 0xbdd2d3e2, v220
	v_fmamk_f32 v147, v147, 0xbdd2d3e2, v220
	v_mul_f32_e32 v107, v144, v107
	v_mul_f32_e32 v147, v145, v147
	v_exp_f32_e32 v107, v107
	v_exp_f32_e32 v147, v147
	v_mov_b32_dpp v142, v132 row_shr:1 row_mask:0xf bank_mask:0xf bound_ctrl:0
	v_add_f32_e32 v107, 1.0, v107
	v_add_f32_e32 v147, 1.0, v147
	v_mov_b32_dpp v143, v133 row_shr:1 row_mask:0xf bank_mask:0xf bound_ctrl:0
	v_rcp_f32_e32 v107, v107
	v_rcp_f32_e32 v147, v147
	v_mov_b32_dpp v138, v124 row_shr:1 row_mask:0xf bank_mask:0xf bound_ctrl:0
	v_mov_b32_dpp v139, v125 row_shr:1 row_mask:0xf bank_mask:0xf bound_ctrl:0
	v_pk_fma_f32 v[142:143], v[76:77], v[142:143], v[80:81]
	v_mul_f32_e32 v107, v144, v107
	v_pk_fma_f32 v[142:143], v[100:101], v[138:139], v[142:143]
	v_mul_f32_e32 v144, v145, v147
	v_pk_fma_f32 v[148:149], v[96:97], v[136:137], v[142:143]
	v_mul_f32_e32 v145, v148, v148
	v_mul_f32_e32 v147, v149, v149
	v_fmamk_f32 v145, v145, 0xbdd2d3e2, v220
	v_fmamk_f32 v147, v147, 0xbdd2d3e2, v220
	v_mul_f32_e32 v145, v148, v145
	v_mul_f32_e32 v147, v149, v147
	v_exp_f32_e32 v145, v145
	v_exp_f32_e32 v147, v147
	v_mov_b32_dpp v150, v126 row_shr:1 row_mask:0xf bank_mask:0xf bound_ctrl:0
	v_mov_b32_dpp v151, v127 row_shr:1 row_mask:0xf bank_mask:0xf bound_ctrl:0
	v_add_f32_e32 v145, 1.0, v145
	v_add_f32_e32 v147, 1.0, v147
	v_mov_b32_dpp v140, v118 row_shr:1 row_mask:0xf bank_mask:0xf bound_ctrl:0
	v_mov_b32_dpp v141, v119 row_shr:1 row_mask:0xf bank_mask:0xf bound_ctrl:0
	v_pk_fma_f32 v[150:151], v[86:87], v[150:151], v[90:91]
	v_rcp_f32_e32 v145, v145
	v_rcp_f32_e32 v147, v147
	v_mov_b32_dpp v152, v128 row_shr:1 row_mask:0xf bank_mask:0xf bound_ctrl:0
	v_mov_b32_dpp v153, v129 row_shr:1 row_mask:0xf bank_mask:0xf bound_ctrl:0
	v_pk_fma_f32 v[150:151], v[82:83], v[140:141], v[150:151]
	v_mov_b32_dpp v142, v120 row_shr:1 row_mask:0xf bank_mask:0xf bound_ctrl:0
	v_mov_b32_dpp v143, v121 row_shr:1 row_mask:0xf bank_mask:0xf bound_ctrl:0
	v_pk_fma_f32 v[152:153], v[88:89], v[152:153], v[92:93]
	v_pk_fma_f32 v[150:151], v[70:71], v[114:115], v[150:151]
	v_pk_fma_f32 v[152:153], v[84:85], v[142:143], v[152:153]
	v_mul_f32_e32 v107, v107, v150
	v_mul_f32_e32 v144, v144, v151
	v_pk_fma_f32 v[152:153], v[72:73], v[116:117], v[152:153]
	v_cvt_pk_bf16_f32 v144, v107, v144
	v_mul_f32_e32 v107, v148, v145
	v_mul_f32_e32 v145, v149, v147
	v_mul_f32_e32 v145, v145, v153
	v_mul_f32_e32 v107, v107, v152
	v_cvt_pk_bf16_f32 v145, v107, v145
	s_and_saveexec_b64 s[30:31], s[4:5]
	s_cbranch_execz .LBB0_246
	v_mul_lo_u32 v107, v238, s23
	v_add_lshl_u32 v148, v107, v192, 1
	v_mov_b32_e32 v149, v1
	v_lshl_add_u64 v[148:149], s[8:9], 0, v[148:149]
	global_store_dwordx2 v[148:149], v[144:145], off

.LBB0_248:
	s_or_b64 exec, exec, s[30:31]
	v_pk_fma_f32 v[134:135], v[74:75], v[134:135], v[78:79]
	v_pk_fma_f32 v[108:109], v[76:77], v[136:137], v[80:81]
	v_pk_fma_f32 v[134:135], v[98:99], v[110:111], v[134:135]
	v_pk_fma_f32 v[76:77], v[76:77], v[112:113], v[80:81]
	v_pk_fma_f32 v[134:135], v[94:95], v[130:131], v[134:135]
	v_pk_fma_f32 v[80:81], v[86:87], v[114:115], v[90:91]
	v_pk_fma_f32 v[86:87], v[86:87], v[102:103], v[90:91]
	v_pk_fma_f32 v[80:81], v[82:83], v[102:103], v[80:81]
	v_pk_fma_f32 v[82:83], v[82:83], v[126:127], v[86:87]
	v_mul_f32_e32 v86, v134, v134
	v_fmamk_f32 v86, v86, 0xbdd2d3e2, v220
	v_mul_f32_e32 v86, v134, v86
	v_exp_f32_e32 v86, v86
	v_pk_fma_f32 v[74:75], v[74:75], v[110:111], v[78:79]
	v_pk_fma_f32 v[78:79], v[88:89], v[116:117], v[92:93]
	v_pk_fma_f32 v[88:89], v[88:89], v[104:105], v[92:93]
	v_mul_f32_e32 v87, v135, v135
	v_pk_fma_f32 v[78:79], v[84:85], v[104:105], v[78:79]
	v_pk_fma_f32 v[84:85], v[84:85], v[128:129], v[88:89]
	v_fmamk_f32 v87, v87, 0xbdd2d3e2, v220
	v_pk_fma_f32 v[78:79], v[72:73], v[128:129], v[78:79]
	v_mul_f32_e32 v87, v135, v87
	v_pk_fma_f32 v[72:73], v[72:73], v[120:121], v[84:85]
	v_add_f32_e32 v84, 1.0, v86
	v_exp_f32_e32 v87, v87
	v_rcp_f32_e32 v84, v84
	v_pk_fma_f32 v[108:109], v[100:101], v[112:113], v[108:109]
	v_pk_fma_f32 v[80:81], v[70:71], v[126:127], v[80:81]
	v_pk_fma_f32 v[108:109], v[96:97], v[132:133], v[108:109]
	v_pk_fma_f32 v[70:71], v[70:71], v[118:119], v[82:83]
	v_mul_f32_e32 v83, v108, v108
	v_add_f32_e32 v85, 1.0, v87
	v_mul_f32_e32 v82, v134, v84
	v_fmamk_f32 v83, v83, 0xbdd2d3e2, v220
	v_mul_f32_e32 v84, v109, v109
	v_rcp_f32_e32 v85, v85
	v_mul_f32_e32 v83, v108, v83
	v_fmamk_f32 v84, v84, 0xbdd2d3e2, v220
	v_exp_f32_e32 v83, v83
	v_mul_f32_e32 v84, v109, v84
	v_exp_f32_e32 v84, v84
	v_mul_f32_e32 v80, v80, v82
	v_mul_f32_e32 v82, v135, v85
	v_mul_f32_e32 v81, v81, v82
	v_add_f32_e32 v82, 1.0, v83
	v_rcp_f32_e32 v82, v82
	v_add_f32_e32 v83, 1.0, v84
	v_rcp_f32_e32 v83, v83
	v_cvt_pk_bf16_f32 v80, v80, v81
	v_mul_f32_e32 v81, v108, v82
	v_pk_fma_f32 v[74:75], v[98:99], v[130:131], v[74:75]
	v_mul_f32_e32 v78, v78, v81
	v_mul_f32_e32 v81, v109, v83
	v_pk_fma_f32 v[74:75], v[94:95], v[122:123], v[74:75]
	v_mul_f32_e32 v79, v79, v81
	v_cvt_pk_bf16_f32 v81, v78, v79
	v_mov_b32_e32 v78, 0xbe800
	v_lshl_add_u32 v102, v146, 1, v78
	v_mul_f32_e32 v78, v74, v74
	v_fmamk_f32 v78, v78, 0xbdd2d3e2, v220
	v_mul_f32_e32 v78, v74, v78
	v_exp_f32_e32 v82, v78
	v_mul_f32_e32 v78, v75, v75
	v_fmamk_f32 v78, v78, 0xbdd2d3e2, v220
	v_mul_f32_e32 v78, v75, v78
	v_exp_f32_e32 v83, v78
	v_add_f32_e32 v82, 1.0, v82
	v_rcp_f32_e32 v82, v82
	v_pk_fma_f32 v[76:77], v[100:101], v[132:133], v[76:77]
	v_add_f32_e32 v83, 1.0, v83
	v_rcp_f32_e32 v83, v83
	v_pk_fma_f32 v[76:77], v[96:97], v[124:125], v[76:77]
	v_mov_b32_e32 v103, v1
	v_mul_f32_e32 v74, v74, v82
	v_lshl_add_u64 v[78:79], s[8:9], 0, v[102:103]
	v_mul_f32_e32 v70, v70, v74
	v_mul_f32_e32 v74, v75, v83
	v_mul_f32_e32 v75, v76, v76
	global_store_dwordx2 v[78:79], v[80:81], off
	v_fmamk_f32 v75, v75, 0xbdd2d3e2, v220
	v_mul_f32_e32 v78, v77, v77
	v_mul_f32_e32 v75, v76, v75
	v_fmamk_f32 v78, v78, 0xbdd2d3e2, v220
	v_exp_f32_e32 v75, v75
	v_mul_f32_e32 v78, v77, v78
	v_exp_f32_e32 v78, v78
	v_mul_f32_e32 v71, v71, v74
	v_add_f32_e32 v74, 1.0, v75
	v_rcp_f32_e32 v74, v74
	v_add_f32_e32 v75, 1.0, v78
	v_rcp_f32_e32 v75, v75
	v_cvt_pk_bf16_f32 v70, v70, v71
	v_mul_f32_e32 v71, v76, v74
	v_mul_f32_e32 v71, v72, v71
	v_mul_f32_e32 v72, v77, v75
	v_add_u32_e32 v103, 0x60000, v146
	v_mul_f32_e32 v72, v73, v72
	v_lshlrev_b32_e32 v104, 1, v103
	v_mov_b32_e32 v105, v1
	v_cvt_pk_bf16_f32 v71, v71, v72
	v_lshl_add_u64 v[72:73], s[8:9], 0, v[104:105]
	global_store_dwordx2 v[72:73], v[70:71], off
	global_load_dwordx4 v[78:81], v[206:207], off offset:16
	global_load_dwordx4 v[82:85], v[200:201], off offset:16
	global_load_dwordx4 v[74:77], v[202:203], off offset:16
	s_nop 0
	global_load_dwordx4 v[70:73], v[208:209], off offset:16
	global_load_dwordx4 v[94:97], v[214:215], off offset:16
	global_load_dwordx4 v[98:101], v[204:205], off offset:16
	global_load_dwordx4 v[90:93], v[210:211], off offset:16
	global_load_dwordx4 v[86:89], v[212:213], off offset:16
	v_mov_b32_dpp v112, v22 row_shr:1 row_mask:0xf bank_mask:0xf bound_ctrl:0
	v_mov_b32_dpp v113, v23 row_shr:1 row_mask:0xf bank_mask:0xf bound_ctrl:0
	v_mov_b32_dpp v108, v34 row_shr:1 row_mask:0xf bank_mask:0xf bound_ctrl:0
	v_mov_b32_dpp v109, v35 row_shr:1 row_mask:0xf bank_mask:0xf bound_ctrl:0
	v_mov_b32_dpp v114, v24 row_shr:1 row_mask:0xf bank_mask:0xf bound_ctrl:0
	v_mov_b32_dpp v115, v25 row_shr:1 row_mask:0xf bank_mask:0xf bound_ctrl:0
	v_mov_b32_dpp v110, v36 row_shr:1 row_mask:0xf bank_mask:0xf bound_ctrl:0
	v_mov_b32_dpp v111, v37 row_shr:1 row_mask:0xf bank_mask:0xf bound_ctrl:0
	v_mov_b32_dpp v120, v18 row_shr:1 row_mask:0xf bank_mask:0xf bound_ctrl:0
	v_mov_b32_dpp v121, v19 row_shr:1 row_mask:0xf bank_mask:0xf bound_ctrl:0
	v_mov_b32_dpp v122, v20 row_shr:1 row_mask:0xf bank_mask:0xf bound_ctrl:0
	s_waitcnt vmcnt(0) lgkmcnt(0)
	v_pk_fma_f32 v[112:113], v[78:79], v[112:113], v[82:83]
	s_nop 0
	v_pk_fma_f32 v[112:113], v[74:75], v[108:109], v[112:113]
	v_pk_fma_f32 v[114:115], v[80:81], v[114:115], v[84:85]
	v_pk_fma_f32 v[116:117], v[58:59], v[70:71], v[112:113]
	v_pk_fma_f32 v[114:115], v[76:77], v[110:111], v[114:115]
	v_mul_f32_e32 v105, v116, v116
	v_fmamk_f32 v105, v105, 0xbdd2d3e2, v220
	v_mul_f32_e32 v107, v117, v117
	v_mul_f32_e32 v105, v116, v105
	v_fmamk_f32 v107, v107, 0xbdd2d3e2, v220
	v_exp_f32_e32 v105, v105
	v_mul_f32_e32 v107, v117, v107
	v_exp_f32_e32 v107, v107
	v_pk_fma_f32 v[118:119], v[60:61], v[72:73], v[114:115]
	v_add_f32_e32 v105, 1.0, v105
	v_rcp_f32_e32 v105, v105
	v_add_f32_e32 v107, 1.0, v107
	v_rcp_f32_e32 v107, v107
	v_mul_f32_e32 v105, v116, v105
	v_mul_f32_e32 v116, v118, v118
	v_mul_f32_e32 v107, v117, v107
	v_fmamk_f32 v116, v116, 0xbdd2d3e2, v220
	v_mul_f32_e32 v117, v119, v119
	v_mul_f32_e32 v116, v118, v116
	v_fmamk_f32 v117, v117, 0xbdd2d3e2, v220
	v_exp_f32_e32 v116, v116
	v_mul_f32_e32 v117, v119, v117
	v_exp_f32_e32 v117, v117
	v_mov_b32_dpp v112, v30 row_shr:1 row_mask:0xf bank_mask:0xf bound_ctrl:0
	v_mov_b32_dpp v113, v31 row_shr:1 row_mask:0xf bank_mask:0xf bound_ctrl:0
	v_pk_fma_f32 v[120:121], v[98:99], v[120:121], v[94:95]
	v_add_f32_e32 v116, 1.0, v116
	v_pk_fma_f32 v[120:121], v[90:91], v[112:113], v[120:121]
	v_pk_fma_f32 v[120:121], v[54:55], v[86:87], v[120:121]
	v_mul_f32_e32 v105, v105, v120
	v_rcp_f32_e32 v120, v116
	v_add_f32_e32 v116, 1.0, v117
	v_rcp_f32_e32 v117, v116
	v_mov_b32_dpp v123, v21 row_shr:1 row_mask:0xf bank_mask:0xf bound_ctrl:0
	v_mov_b32_dpp v114, v32 row_shr:1 row_mask:0xf bank_mask:0xf bound_ctrl:0
	v_mov_b32_dpp v115, v33 row_shr:1 row_mask:0xf bank_mask:0xf bound_ctrl:0
	v_pk_fma_f32 v[122:123], v[100:101], v[122:123], v[96:97]
	v_mul_f32_e32 v107, v107, v121
	v_pk_fma_f32 v[122:123], v[92:93], v[114:115], v[122:123]
	v_cvt_pk_bf16_f32 v116, v105, v107
	v_mul_f32_e32 v105, v118, v120
	v_pk_fma_f32 v[122:123], v[56:57], v[88:89], v[122:123]
	v_mul_f32_e32 v107, v119, v117
	v_mul_f32_e32 v105, v105, v122
	v_mul_f32_e32 v107, v107, v123
	v_cvt_pk_bf16_f32 v117, v105, v107
	s_and_saveexec_b64 s[30:31], s[4:5]
	s_cbranch_execz .LBB0_250
	v_mad_u64_u32 v[118:119], s[34:35], v237, s23, v[192:193]
	v_lshl_or_b32 v118, v118, 1, 8
	v_mov_b32_e32 v119, v1
	v_lshl_add_u64 v[118:119], s[8:9], 0, v[118:119]
	global_store_dwordx2 v[118:119], v[116:117], off

.LBB0_252:
	s_or_b64 exec, exec, s[30:31]
	v_pk_fma_f32 v[58:59], v[58:59], v[78:79], v[82:83]
	v_pk_fma_f32 v[60:61], v[60:61], v[80:81], v[84:85]
	v_pk_fma_f32 v[58:59], v[66:67], v[74:75], v[58:59]
	v_pk_fma_f32 v[66:67], v[66:67], v[78:79], v[82:83]
	v_pk_fma_f32 v[60:61], v[68:69], v[76:77], v[60:61]
	v_pk_fma_f32 v[58:59], v[22:23], v[70:71], v[58:59]
	v_pk_fma_f32 v[68:69], v[68:69], v[80:81], v[84:85]
	v_pk_fma_f32 v[22:23], v[22:23], v[74:75], v[66:67]
	v_pk_fma_f32 v[60:61], v[24:25], v[72:73], v[60:61]
	v_pk_fma_f32 v[24:25], v[24:25], v[76:77], v[68:69]
	v_pk_fma_f32 v[22:23], v[34:35], v[70:71], v[22:23]
	v_pk_fma_f32 v[34:35], v[56:57], v[100:101], v[96:97]
	v_pk_fma_f32 v[24:25], v[36:37], v[72:73], v[24:25]
	v_pk_fma_f32 v[36:37], v[54:55], v[98:99], v[94:95]
	v_pk_fma_f32 v[34:35], v[64:65], v[92:93], v[34:35]
	v_pk_fma_f32 v[54:55], v[64:65], v[100:101], v[96:97]
	v_pk_fma_f32 v[34:35], v[20:21], v[88:89], v[34:35]
	v_pk_fma_f32 v[20:21], v[20:21], v[92:93], v[54:55]
	v_mul_f32_e32 v54, v58, v58
	v_mul_f32_e32 v55, v59, v59
	v_fmamk_f32 v54, v54, 0xbdd2d3e2, v220
	v_fmamk_f32 v55, v55, 0xbdd2d3e2, v220
	v_mul_f32_e32 v54, v58, v54
	v_mul_f32_e32 v55, v59, v55
	v_exp_f32_e32 v54, v54
	v_exp_f32_e32 v55, v55
	v_pk_fma_f32 v[20:21], v[32:33], v[88:89], v[20:21]
	v_pk_fma_f32 v[36:37], v[62:63], v[90:91], v[36:37]
	v_add_f32_e32 v32, 1.0, v54
	v_add_f32_e32 v33, 1.0, v55
	v_rcp_f32_e32 v32, v32
	v_rcp_f32_e32 v33, v33
	v_pk_fma_f32 v[56:57], v[62:63], v[98:99], v[94:95]
	v_pk_fma_f32 v[36:37], v[18:19], v[86:87], v[36:37]
	v_pk_fma_f32 v[18:19], v[18:19], v[90:91], v[56:57]
	v_or_b32_e32 v0, 8, v0
	v_pk_fma_f32 v[18:19], v[30:31], v[86:87], v[18:19]
	v_mul_f32_e32 v30, v58, v32
	v_mul_f32_e32 v31, v59, v33
	v_mul_f32_e32 v32, v60, v60
	v_mul_f32_e32 v33, v61, v61
	v_fmamk_f32 v32, v32, 0xbdd2d3e2, v220
	v_fmamk_f32 v33, v33, 0xbdd2d3e2, v220
	v_mul_f32_e32 v32, v60, v32
	v_mul_f32_e32 v33, v61, v33
	v_exp_f32_e32 v32, v32
	v_exp_f32_e32 v33, v33
	v_mul_f32_e32 v30, v36, v30
	v_mul_f32_e32 v31, v37, v31
	v_add_f32_e32 v32, 1.0, v32
	v_add_f32_e32 v33, 1.0, v33
	v_rcp_f32_e32 v32, v32
	v_rcp_f32_e32 v33, v33
	v_cvt_pk_bf16_f32 v30, v30, v31
	v_mul_f32_e32 v31, v60, v32
	v_mul_f32_e32 v32, v61, v33
	v_mul_f32_e32 v31, v34, v31
	v_mul_f32_e32 v32, v35, v32
	v_cvt_pk_bf16_f32 v31, v31, v32
	v_mul_f32_e32 v32, v22, v22
	v_fmamk_f32 v32, v32, 0xbdd2d3e2, v220
	v_mul_f32_e32 v32, v22, v32
	v_exp_f32_e32 v34, v32
	v_mul_f32_e32 v32, v23, v23
	v_fmamk_f32 v32, v32, 0xbdd2d3e2, v220
	v_mul_f32_e32 v32, v23, v32
	v_exp_f32_e32 v35, v32
	v_lshl_add_u64 v[32:33], s[8:9], 0, v[0:1]
	v_add_f32_e32 v0, 1.0, v34
	v_rcp_f32_e32 v0, v0
	v_add_f32_e32 v34, 1.0, v35
	v_rcp_f32_e32 v34, v34
	global_store_dwordx2 v[32:33], v[30:31], off
	v_mul_f32_e32 v0, v22, v0
	v_mul_f32_e32 v0, v18, v0
	v_mul_f32_e32 v18, v23, v34
	v_mul_f32_e32 v22, v24, v24
	v_mul_f32_e32 v23, v25, v25
	v_fmamk_f32 v22, v22, 0xbdd2d3e2, v220
	v_fmamk_f32 v23, v23, 0xbdd2d3e2, v220
	v_mul_f32_e32 v22, v24, v22
	v_mul_f32_e32 v23, v25, v23
	v_exp_f32_e32 v22, v22
	v_exp_f32_e32 v23, v23
	v_mul_f32_e32 v18, v19, v18
	v_cvt_pk_bf16_f32 v18, v0, v18
	v_add_f32_e32 v19, 1.0, v22
	v_add_f32_e32 v22, 1.0, v23
	v_rcp_f32_e32 v19, v19
	v_rcp_f32_e32 v22, v22
	v_mul_f32_e32 v0, v24, v19
	v_mul_f32_e32 v19, v25, v22
	v_mul_f32_e32 v0, v20, v0
	v_mul_f32_e32 v19, v21, v19
	v_cvt_pk_bf16_f32 v19, v0, v19
	v_or_b32_e32 v0, 8, v106
	v_lshl_add_u64 v[20:21], s[8:9], 0, v[0:1]
	global_store_dwordx2 v[20:21], v[18:19], off
	v_mov_b32_dpp v22, v6 row_shr:1 row_mask:0xf bank_mask:0xf bound_ctrl:0
	v_mov_b32_dpp v23, v7 row_shr:1 row_mask:0xf bank_mask:0xf bound_ctrl:0
	v_mov_b32_dpp v18, v14 row_shr:1 row_mask:0xf bank_mask:0xf bound_ctrl:0
	v_mov_b32_dpp v19, v15 row_shr:1 row_mask:0xf bank_mask:0xf bound_ctrl:0
	v_pk_fma_f32 v[22:23], v[78:79], v[22:23], v[82:83]
	v_pk_fma_f32 v[22:23], v[74:75], v[18:19], v[22:23]
	v_pk_fma_f32 v[30:31], v[38:39], v[70:71], v[22:23]
	v_mul_f32_e32 v0, v30, v30
	v_fmamk_f32 v0, v0, 0xbdd2d3e2, v220
	v_mul_f32_e32 v54, v31, v31
	v_mul_f32_e32 v0, v30, v0
	v_fmamk_f32 v54, v54, 0xbdd2d3e2, v220
	v_exp_f32_e32 v0, v0
	v_mul_f32_e32 v54, v31, v54
	v_exp_f32_e32 v54, v54
	v_add_f32_e32 v0, 1.0, v0
	v_rcp_f32_e32 v0, v0
	v_add_f32_e32 v54, 1.0, v54
	v_mov_b32_dpp v24, v8 row_shr:1 row_mask:0xf bank_mask:0xf bound_ctrl:0
	v_mov_b32_dpp v25, v9 row_shr:1 row_mask:0xf bank_mask:0xf bound_ctrl:0
	v_mov_b32_dpp v34, v10 row_shr:1 row_mask:0xf bank_mask:0xf bound_ctrl:0
	v_mov_b32_dpp v35, v11 row_shr:1 row_mask:0xf bank_mask:0xf bound_ctrl:0
	v_rcp_f32_e32 v54, v54
	v_mov_b32_dpp v20, v16 row_shr:1 row_mask:0xf bank_mask:0xf bound_ctrl:0
	v_mov_b32_dpp v21, v17 row_shr:1 row_mask:0xf bank_mask:0xf bound_ctrl:0
	v_pk_fma_f32 v[24:25], v[80:81], v[24:25], v[84:85]
	v_mov_b32_dpp v22, v26 row_shr:1 row_mask:0xf bank_mask:0xf bound_ctrl:0
	v_mov_b32_dpp v23, v27 row_shr:1 row_mask:0xf bank_mask:0xf bound_ctrl:0
	v_pk_fma_f32 v[34:35], v[98:99], v[34:35], v[94:95]
	v_pk_fma_f32 v[24:25], v[76:77], v[20:21], v[24:25]
	v_pk_fma_f32 v[34:35], v[90:91], v[22:23], v[34:35]
	v_pk_fma_f32 v[32:33], v[40:41], v[72:73], v[24:25]
	v_pk_fma_f32 v[34:35], v[46:47], v[86:87], v[34:35]
	v_mul_f32_e32 v0, v30, v0
	v_mul_f32_e32 v0, v0, v34
	v_mul_f32_e32 v30, v31, v54
	v_mul_f32_e32 v31, v32, v32
	v_mul_f32_e32 v34, v33, v33
	v_fmamk_f32 v31, v31, 0xbdd2d3e2, v220
	v_fmamk_f32 v34, v34, 0xbdd2d3e2, v220
	v_mul_f32_e32 v31, v32, v31
	v_mul_f32_e32 v34, v33, v34
	v_exp_f32_e32 v31, v31
	v_exp_f32_e32 v34, v34
	v_add_f32_e32 v31, 1.0, v31
	v_add_f32_e32 v34, 1.0, v34
	v_rcp_f32_e32 v31, v31
	v_rcp_f32_e32 v34, v34
	v_mov_b32_dpp v36, v12 row_shr:1 row_mask:0xf bank_mask:0xf bound_ctrl:0
	v_mov_b32_dpp v37, v13 row_shr:1 row_mask:0xf bank_mask:0xf bound_ctrl:0
	v_mov_b32_dpp v24, v28 row_shr:1 row_mask:0xf bank_mask:0xf bound_ctrl:0
	v_mov_b32_dpp v25, v29 row_shr:1 row_mask:0xf bank_mask:0xf bound_ctrl:0
	v_pk_fma_f32 v[36:37], v[100:101], v[36:37], v[96:97]
	v_mul_f32_e32 v30, v30, v35
	v_pk_fma_f32 v[36:37], v[92:93], v[24:25], v[36:37]
	v_cvt_pk_bf16_f32 v30, v0, v30
	v_mul_f32_e32 v0, v32, v31
	v_pk_fma_f32 v[36:37], v[48:49], v[88:89], v[36:37]
	v_mul_f32_e32 v31, v33, v34
	v_mul_f32_e32 v31, v31, v37
	v_mul_f32_e32 v0, v0, v36
	v_cvt_pk_bf16_f32 v31, v0, v31
	s_and_saveexec_b64 s[30:31], s[4:5]
	s_cbranch_execz .LBB0_254
	v_mov_b32_e32 v0, 0xffffb808
	v_lshl_add_u32 v0, v103, 1, v0
	v_lshl_add_u64 v[32:33], s[8:9], 0, v[0:1]
	global_store_dwordx2 v[32:33], v[30:31], off
